# P6 pass-0 merge epilogue: both row-halves gate loads issued up front (second half into registers dead across the epilogue), one load-latency exposure per unit instead of two
# speedup vs baseline: 1.0019x; 1.0019x over previous
.LBB0_1268:
	ds_read_b128 v[140:143], v149
	ds_read_b128 v[152:155], v149 offset:1024
	ds_read_b128 v[156:159], v149 offset:2048
	ds_read_b128 v[160:163], v149 offset:3072
	s_add_u32 s22, s10, 0xfffe0080
	s_addc_u32 s23, s11, -1
	s_cmp_eq_u32 s44, 4
	s_cselect_b32 s25, s13, s23
	s_cselect_b32 s24, s40, s22
	s_cselect_b32 s23, s15, s43
	s_cselect_b32 s22, s41, s42
	v_lshl_add_u64 v[144:145], s[10:11], 0, v[136:137]
	s_add_i32 m0, s1, 0xc000
	ds_read_b128 v[164:167], v150
	ds_read_b128 v[168:171], v150 offset:1024
	ds_read_b128 v[172:175], v150 offset:2048
	ds_read_b128 v[180:183], v150 offset:3072
	ds_read_b128 v[184:187], v150 offset:4096
	ds_read_b128 v[188:191], v150 offset:5120
	ds_read_b128 v[192:195], v150 offset:6144
	ds_read_b128 v[196:199], v150 offset:7168
	global_load_lds_dwordx4 v[144:145], off
	v_lshl_add_u64 v[144:145], s[10:11], 0, v[138:139]
	s_add_i32 m0, s1, 0xe000
	s_nop 0
	global_load_lds_dwordx4 v[144:145], off
	s_waitcnt lgkmcnt(8)
	s_barrier
	s_waitcnt lgkmcnt(0)
	s_setprio 1
	s_waitcnt lgkmcnt(0)
	v_mfma_f32_16x16x32_bf16 v[124:127], v[140:143], v[164:167], v[124:127]
	v_mfma_f32_16x16x32_bf16 v[120:123], v[156:159], v[164:167], v[120:123]
	v_mfma_f32_16x16x32_bf16 v[112:115], v[140:143], v[172:175], v[112:115]
	v_mfma_f32_16x16x32_bf16 v[104:107], v[156:159], v[172:175], v[104:107]
	v_mfma_f32_16x16x32_bf16 v[96:99], v[140:143], v[184:187], v[96:99]
	v_mfma_f32_16x16x32_bf16 v[88:91], v[156:159], v[184:187], v[88:91]
	v_mfma_f32_16x16x32_bf16 v[80:83], v[140:143], v[192:195], v[80:83]
	v_mfma_f32_16x16x32_bf16 v[72:75], v[156:159], v[192:195], v[72:75]
	v_mfma_f32_16x16x32_bf16 v[124:127], v[152:155], v[168:171], v[124:127]
	v_mfma_f32_16x16x32_bf16 v[120:123], v[160:163], v[168:171], v[120:123]
	v_mfma_f32_16x16x32_bf16 v[112:115], v[152:155], v[180:183], v[112:115]
	v_mfma_f32_16x16x32_bf16 v[104:107], v[160:163], v[180:183], v[104:107]
	v_mfma_f32_16x16x32_bf16 v[96:99], v[152:155], v[188:191], v[96:99]
	v_mfma_f32_16x16x32_bf16 v[88:91], v[160:163], v[188:191], v[88:91]
	v_mfma_f32_16x16x32_bf16 v[80:83], v[152:155], v[196:199], v[80:83]
	v_mfma_f32_16x16x32_bf16 v[72:75], v[160:163], v[196:199], v[72:75]
	s_setprio 0
	s_barrier
	s_add_i32 s45, s35, s27
	v_lshl_add_u64 v[144:145], s[22:23], 0, v[132:133]
	s_mov_b32 m0, s45
	ds_read_b128 v[200:203], v151
	ds_read_b128 v[204:207], v151 offset:1024
	ds_read_b128 v[208:211], v151 offset:2048
	ds_read_b128 v[212:215], v151 offset:3072
	global_load_lds_dwordx4 v[144:145], off
	v_lshl_add_u64 v[176:177], s[22:23], 0, v[128:129]
	s_add_i32 m0, s45, 0x2000
	s_nop 0
	global_load_lds_dwordx4 v[176:177], off
	s_barrier
	s_waitcnt lgkmcnt(0)
	s_setprio 1
	s_waitcnt lgkmcnt(0)
	v_mfma_f32_16x16x32_bf16 v[116:119], v[200:203], v[164:167], v[116:119]
	v_mfma_f32_16x16x32_bf16 v[108:111], v[208:211], v[164:167], v[108:111]
	v_mfma_f32_16x16x32_bf16 v[100:103], v[200:203], v[172:175], v[100:103]
	v_mfma_f32_16x16x32_bf16 v[92:95], v[208:211], v[172:175], v[92:95]
	v_mfma_f32_16x16x32_bf16 v[84:87], v[200:203], v[184:187], v[84:87]
	v_mfma_f32_16x16x32_bf16 v[76:79], v[208:211], v[184:187], v[76:79]
	v_mfma_f32_16x16x32_bf16 v[68:71], v[200:203], v[192:195], v[68:71]
	v_mfma_f32_16x16x32_bf16 v[64:67], v[208:211], v[192:195], v[64:67]
	v_mfma_f32_16x16x32_bf16 v[116:119], v[204:207], v[168:171], v[116:119]
	v_mfma_f32_16x16x32_bf16 v[108:111], v[212:215], v[168:171], v[108:111]
	v_mfma_f32_16x16x32_bf16 v[100:103], v[204:207], v[180:183], v[100:103]
	v_mfma_f32_16x16x32_bf16 v[92:95], v[212:215], v[180:183], v[92:95]
	v_mfma_f32_16x16x32_bf16 v[84:87], v[204:207], v[188:191], v[84:87]
	v_mfma_f32_16x16x32_bf16 v[76:79], v[212:215], v[188:191], v[76:79]
	v_mfma_f32_16x16x32_bf16 v[68:71], v[204:207], v[196:199], v[68:71]
	v_mfma_f32_16x16x32_bf16 v[64:67], v[212:215], v[196:199], v[64:67]
	s_setprio 0
	s_mov_b32 m0, s1
	v_lshl_add_u64 v[216:217], s[24:25], 0, v[134:135]
	s_barrier
	ds_read_b128 v[164:167], v150 offset:16384
	ds_read_b128 v[168:171], v150 offset:17408
	ds_read_b128 v[172:175], v150 offset:18432
	ds_read_b128 v[180:183], v150 offset:19456
	ds_read_b128 v[184:187], v150 offset:20480
	ds_read_b128 v[188:191], v150 offset:21504
	ds_read_b128 v[192:195], v150 offset:22528
	ds_read_b128 v[196:199], v150 offset:23552
	global_load_lds_dwordx4 v[216:217], off
	v_lshl_add_u64 v[218:219], s[24:25], 0, v[130:131]
	s_mov_b32 m0, s7
	s_nop 0
	global_load_lds_dwordx4 v[218:219], off
	s_barrier
	s_waitcnt lgkmcnt(0)
	s_setprio 1
	s_waitcnt lgkmcnt(0)
	v_mfma_f32_16x16x32_bf16 v[60:63], v[140:143], v[164:167], v[60:63]
	v_mfma_f32_16x16x32_bf16 v[56:59], v[156:159], v[164:167], v[56:59]
	v_mfma_f32_16x16x32_bf16 v[48:51], v[140:143], v[172:175], v[48:51]
	v_mfma_f32_16x16x32_bf16 v[40:43], v[156:159], v[172:175], v[40:43]
	v_mfma_f32_16x16x32_bf16 v[32:35], v[140:143], v[184:187], v[32:35]
	v_mfma_f32_16x16x32_bf16 v[24:27], v[156:159], v[184:187], v[24:27]
	v_mfma_f32_16x16x32_bf16 v[16:19], v[140:143], v[192:195], v[16:19]
	v_mfma_f32_16x16x32_bf16 v[8:11], v[156:159], v[192:195], v[8:11]
	v_mfma_f32_16x16x32_bf16 v[60:63], v[152:155], v[168:171], v[60:63]
	v_mfma_f32_16x16x32_bf16 v[56:59], v[160:163], v[168:171], v[56:59]
	v_mfma_f32_16x16x32_bf16 v[48:51], v[152:155], v[180:183], v[48:51]
	v_mfma_f32_16x16x32_bf16 v[40:43], v[160:163], v[180:183], v[40:43]
	v_mfma_f32_16x16x32_bf16 v[32:35], v[152:155], v[188:191], v[32:35]
	v_mfma_f32_16x16x32_bf16 v[24:27], v[160:163], v[188:191], v[24:27]
	v_mfma_f32_16x16x32_bf16 v[16:19], v[152:155], v[196:199], v[16:19]
	v_mfma_f32_16x16x32_bf16 v[8:11], v[160:163], v[196:199], v[8:11]
	s_setprio 0
	s_barrier
	s_add_u32 s46, s22, 0x20000
	s_addc_u32 s47, s23, 0
	s_add_i32 s45, s36, s27
	v_lshl_add_u64 v[140:141], s[46:47], 0, v[132:133]
	s_mov_b32 m0, s45
	s_nop 0
	global_load_lds_dwordx4 v[140:141], off
	v_lshl_add_u64 v[140:141], s[46:47], 0, v[128:129]
	s_add_i32 m0, s45, 0x2000
	s_nop 0
	global_load_lds_dwordx4 v[140:141], off
	s_waitcnt vmcnt(6)
	s_barrier
	s_setprio 1
	v_mfma_f32_16x16x32_bf16 v[52:55], v[200:203], v[164:167], v[52:55]
	v_mfma_f32_16x16x32_bf16 v[44:47], v[208:211], v[164:167], v[44:47]
	v_mfma_f32_16x16x32_bf16 v[36:39], v[200:203], v[172:175], v[36:39]
	v_mfma_f32_16x16x32_bf16 v[28:31], v[208:211], v[172:175], v[28:31]
	v_mfma_f32_16x16x32_bf16 v[20:23], v[200:203], v[184:187], v[20:23]
	v_mfma_f32_16x16x32_bf16 v[12:15], v[208:211], v[184:187], v[12:15]
	v_mfma_f32_16x16x32_bf16 v[4:7], v[200:203], v[192:195], v[4:7]
	v_mfma_f32_16x16x32_bf16 v[0:3], v[208:211], v[192:195], v[0:3]
	v_mfma_f32_16x16x32_bf16 v[52:55], v[204:207], v[168:171], v[52:55]
	v_mfma_f32_16x16x32_bf16 v[44:47], v[212:215], v[168:171], v[44:47]
	v_mfma_f32_16x16x32_bf16 v[36:39], v[204:207], v[180:183], v[36:39]
	v_mfma_f32_16x16x32_bf16 v[28:31], v[212:215], v[180:183], v[28:31]
	v_mfma_f32_16x16x32_bf16 v[20:23], v[204:207], v[188:191], v[20:23]
	v_mfma_f32_16x16x32_bf16 v[12:15], v[212:215], v[188:191], v[12:15]
	v_mfma_f32_16x16x32_bf16 v[4:7], v[204:207], v[196:199], v[4:7]
	v_mfma_f32_16x16x32_bf16 v[0:3], v[212:215], v[196:199], v[0:3]
	s_setprio 0
	s_add_i32 s45, 0, 0x18000
	v_add_u32_e32 v160, s45, v147
	s_barrier
	ds_read_b128 v[140:143], v160
	ds_read_b128 v[152:155], v160 offset:1024
	ds_read_b128 v[156:159], v160 offset:2048
	ds_read_b128 v[160:163], v160 offset:3072
	s_add_u32 s24, s24, 0x20000
	s_addc_u32 s25, s25, 0
	s_mov_b32 m0, s28
	v_lshl_add_u64 v[200:201], s[24:25], 0, v[134:135]
	ds_read_b128 v[164:167], v150 offset:32768
	ds_read_b128 v[168:171], v150 offset:33792
	ds_read_b128 v[172:175], v150 offset:34816
	ds_read_b128 v[180:183], v150 offset:35840
	ds_read_b128 v[184:187], v150 offset:36864
	ds_read_b128 v[188:191], v150 offset:37888
	ds_read_b128 v[192:195], v150 offset:38912
	ds_read_b128 v[196:199], v150 offset:39936
	global_load_lds_dwordx4 v[200:201], off
	v_lshl_add_u64 v[200:201], s[24:25], 0, v[130:131]
	s_mov_b32 m0, s29
	s_nop 0
	global_load_lds_dwordx4 v[200:201], off
	s_waitcnt lgkmcnt(8)
	s_barrier
	s_waitcnt lgkmcnt(0)
	s_setprio 1
	s_waitcnt lgkmcnt(0)
	v_mfma_f32_16x16x32_bf16 v[124:127], v[140:143], v[164:167], v[124:127]
	v_mfma_f32_16x16x32_bf16 v[120:123], v[156:159], v[164:167], v[120:123]
	v_mfma_f32_16x16x32_bf16 v[112:115], v[140:143], v[172:175], v[112:115]
	v_mfma_f32_16x16x32_bf16 v[104:107], v[156:159], v[172:175], v[104:107]
	v_mfma_f32_16x16x32_bf16 v[96:99], v[140:143], v[184:187], v[96:99]
	v_mfma_f32_16x16x32_bf16 v[88:91], v[156:159], v[184:187], v[88:91]
	v_mfma_f32_16x16x32_bf16 v[80:83], v[140:143], v[192:195], v[80:83]
	v_mfma_f32_16x16x32_bf16 v[72:75], v[156:159], v[192:195], v[72:75]
	v_mfma_f32_16x16x32_bf16 v[124:127], v[152:155], v[168:171], v[124:127]
	v_mfma_f32_16x16x32_bf16 v[120:123], v[160:163], v[168:171], v[120:123]
	v_mfma_f32_16x16x32_bf16 v[112:115], v[152:155], v[180:183], v[112:115]
	v_mfma_f32_16x16x32_bf16 v[104:107], v[160:163], v[180:183], v[104:107]
	v_mfma_f32_16x16x32_bf16 v[96:99], v[152:155], v[188:191], v[96:99]
	v_mfma_f32_16x16x32_bf16 v[88:91], v[160:163], v[188:191], v[88:91]
	v_mfma_f32_16x16x32_bf16 v[80:83], v[152:155], v[196:199], v[80:83]
	v_mfma_f32_16x16x32_bf16 v[72:75], v[160:163], v[196:199], v[72:75]
	s_setprio 0
	s_barrier
	s_add_i32 s24, 0, 0x1c000
	s_add_i32 s25, s45, s27
	v_add_u32_e32 v179, s24, v147
	v_lshl_add_u64 v[144:145], v[144:145], 0, s[2:3]
	s_mov_b32 m0, s25
	ds_read_b128 v[200:203], v179
	ds_read_b128 v[204:207], v179 offset:1024
	ds_read_b128 v[208:211], v179 offset:2048
	ds_read_b128 v[212:215], v179 offset:3072
	global_load_lds_dwordx4 v[144:145], off
	v_lshl_add_u64 v[144:145], v[176:177], 0, s[2:3]
	s_add_i32 m0, s25, 0x2000
	s_nop 0
	global_load_lds_dwordx4 v[144:145], off
	s_barrier
	s_waitcnt lgkmcnt(0)
	s_setprio 1
	s_waitcnt lgkmcnt(0)
	v_mfma_f32_16x16x32_bf16 v[116:119], v[200:203], v[164:167], v[116:119]
	v_mfma_f32_16x16x32_bf16 v[108:111], v[208:211], v[164:167], v[108:111]
	v_mfma_f32_16x16x32_bf16 v[100:103], v[200:203], v[172:175], v[100:103]
	v_mfma_f32_16x16x32_bf16 v[92:95], v[208:211], v[172:175], v[92:95]
	v_mfma_f32_16x16x32_bf16 v[84:87], v[200:203], v[184:187], v[84:87]
	v_mfma_f32_16x16x32_bf16 v[76:79], v[208:211], v[184:187], v[76:79]
	v_mfma_f32_16x16x32_bf16 v[68:71], v[200:203], v[192:195], v[68:71]
	v_mfma_f32_16x16x32_bf16 v[64:67], v[208:211], v[192:195], v[64:67]
	v_mfma_f32_16x16x32_bf16 v[116:119], v[204:207], v[168:171], v[116:119]
	v_mfma_f32_16x16x32_bf16 v[108:111], v[212:215], v[168:171], v[108:111]
	v_mfma_f32_16x16x32_bf16 v[100:103], v[204:207], v[180:183], v[100:103]
	v_mfma_f32_16x16x32_bf16 v[92:95], v[212:215], v[180:183], v[92:95]
	v_mfma_f32_16x16x32_bf16 v[84:87], v[204:207], v[188:191], v[84:87]
	v_mfma_f32_16x16x32_bf16 v[76:79], v[212:215], v[188:191], v[76:79]
	v_mfma_f32_16x16x32_bf16 v[68:71], v[204:207], v[196:199], v[68:71]
	v_mfma_f32_16x16x32_bf16 v[64:67], v[212:215], v[196:199], v[64:67]
	s_setprio 0
	s_mov_b32 m0, s31
	v_lshl_add_u64 v[144:145], v[216:217], 0, s[2:3]
	s_barrier
	ds_read_b128 v[164:167], v150 offset:49152
	ds_read_b128 v[168:171], v150 offset:50176
	ds_read_b128 v[172:175], v150 offset:51200
	ds_read_b128 v[180:183], v150 offset:52224
	ds_read_b128 v[184:187], v150 offset:53248
	ds_read_b128 v[188:191], v150 offset:54272
	ds_read_b128 v[192:195], v150 offset:55296
	ds_read_b128 v[196:199], v150 offset:56320
	global_load_lds_dwordx4 v[144:145], off
	v_lshl_add_u64 v[144:145], v[218:219], 0, s[2:3]
	s_mov_b32 m0, s33
	s_nop 0
	global_load_lds_dwordx4 v[144:145], off
	s_barrier
	s_waitcnt lgkmcnt(0)
	s_setprio 1
	s_waitcnt lgkmcnt(0)
	v_mfma_f32_16x16x32_bf16 v[60:63], v[140:143], v[164:167], v[60:63]
	v_mfma_f32_16x16x32_bf16 v[56:59], v[156:159], v[164:167], v[56:59]
	v_mfma_f32_16x16x32_bf16 v[48:51], v[140:143], v[172:175], v[48:51]
	v_mfma_f32_16x16x32_bf16 v[40:43], v[156:159], v[172:175], v[40:43]
	v_mfma_f32_16x16x32_bf16 v[32:35], v[140:143], v[184:187], v[32:35]
	v_mfma_f32_16x16x32_bf16 v[24:27], v[156:159], v[184:187], v[24:27]
	v_mfma_f32_16x16x32_bf16 v[16:19], v[140:143], v[192:195], v[16:19]
	v_mfma_f32_16x16x32_bf16 v[8:11], v[156:159], v[192:195], v[8:11]
	v_mfma_f32_16x16x32_bf16 v[60:63], v[152:155], v[168:171], v[60:63]
	v_mfma_f32_16x16x32_bf16 v[56:59], v[160:163], v[168:171], v[56:59]
	v_mfma_f32_16x16x32_bf16 v[48:51], v[152:155], v[180:183], v[48:51]
	v_mfma_f32_16x16x32_bf16 v[40:43], v[160:163], v[180:183], v[40:43]
	v_mfma_f32_16x16x32_bf16 v[32:35], v[152:155], v[188:191], v[32:35]
	v_mfma_f32_16x16x32_bf16 v[24:27], v[160:163], v[188:191], v[24:27]
	v_mfma_f32_16x16x32_bf16 v[16:19], v[152:155], v[196:199], v[16:19]
	v_mfma_f32_16x16x32_bf16 v[8:11], v[160:163], v[196:199], v[8:11]
	s_setprio 0
	s_barrier
	s_add_u32 s22, s22, 0x20080
	s_addc_u32 s23, s23, 0
	s_add_i32 s24, s24, s27
	v_lshl_add_u64 v[140:141], s[22:23], 0, v[132:133]
	s_mov_b32 m0, s24
	s_nop 0
	global_load_lds_dwordx4 v[140:141], off
	v_lshl_add_u64 v[140:141], s[22:23], 0, v[128:129]
	s_add_i32 m0, s24, 0x2000
	s_nop 0
	global_load_lds_dwordx4 v[140:141], off
	s_waitcnt vmcnt(6)
	s_barrier
	s_setprio 1
	v_mfma_f32_16x16x32_bf16 v[52:55], v[200:203], v[164:167], v[52:55]
	v_mfma_f32_16x16x32_bf16 v[44:47], v[208:211], v[164:167], v[44:47]
	v_mfma_f32_16x16x32_bf16 v[36:39], v[200:203], v[172:175], v[36:39]
	v_mfma_f32_16x16x32_bf16 v[28:31], v[208:211], v[172:175], v[28:31]
	v_mfma_f32_16x16x32_bf16 v[20:23], v[200:203], v[184:187], v[20:23]
	v_mfma_f32_16x16x32_bf16 v[12:15], v[208:211], v[184:187], v[12:15]
	v_mfma_f32_16x16x32_bf16 v[4:7], v[200:203], v[192:195], v[4:7]
	v_mfma_f32_16x16x32_bf16 v[0:3], v[208:211], v[192:195], v[0:3]
	v_mfma_f32_16x16x32_bf16 v[52:55], v[204:207], v[168:171], v[52:55]
	v_mfma_f32_16x16x32_bf16 v[44:47], v[212:215], v[168:171], v[44:47]
	v_mfma_f32_16x16x32_bf16 v[36:39], v[204:207], v[180:183], v[36:39]
	v_mfma_f32_16x16x32_bf16 v[28:31], v[212:215], v[180:183], v[28:31]
	v_mfma_f32_16x16x32_bf16 v[20:23], v[204:207], v[188:191], v[20:23]
	v_mfma_f32_16x16x32_bf16 v[12:15], v[212:215], v[188:191], v[12:15]
	v_mfma_f32_16x16x32_bf16 v[4:7], v[204:207], v[196:199], v[4:7]
	v_mfma_f32_16x16x32_bf16 v[0:3], v[212:215], v[196:199], v[0:3]
	s_setprio 0
	s_add_i32 s44, s44, 2
	s_add_u32 s10, s10, 0x100
	s_addc_u32 s11, s11, 0
	s_add_u32 s42, s42, 0x100
	s_addc_u32 s43, s43, 0
	s_cmp_gt_u32 s44, 5
	s_barrier
	s_cbranch_scc0 .LBB0_1268
	v_lshl_add_u32 v142, s39, 8, v146
	s_nop 0
	v_lshl_or_b32 v140, s38, 8, v148
	v_ashrrev_i32_e32 v143, 31, v142
	s_nop 1
	v_readlane_b32 s46, v252, 13
	v_readlane_b32 s47, v252, 14
	v_ashrrev_i32_e32 v141, 31, v140
	v_lshlrev_b64 v[144:145], 12, v[142:143]
	s_mov_b64 s[42:43], s[46:47]
	v_lshl_add_u64 v[144:145], s[42:43], 0, v[144:145]
	v_lshlrev_b64 v[140:141], 1, v[140:141]
	v_or_b32_e32 v172, 16, v142
	v_lshl_add_u64 v[144:145], v[144:145], 0, v[140:141]
	v_ashrrev_i32_e32 v173, 31, v172
	global_load_dwordx4 v[152:155], v[144:145], off
	global_load_dwordx4 v[156:159], v[144:145], off offset:256
	v_lshlrev_b64 v[144:145], 12, v[172:173]
	v_lshl_add_u64 v[144:145], s[42:43], 0, v[144:145]
	v_lshl_add_u64 v[144:145], v[144:145], 0, v[140:141]
	global_load_dwordx4 v[160:163], v[144:145], off
	global_load_dwordx4 v[164:167], v[144:145], off offset:256
	v_or_b32_e32 v176, 32, v142
	v_ashrrev_i32_e32 v177, 31, v176
	v_lshlrev_b64 v[168:169], 12, v[176:177]
	v_lshl_add_u64 v[168:169], s[42:43], 0, v[168:169]
	v_lshl_add_u64 v[182:183], v[168:169], 0, v[140:141]
	global_load_dwordx4 v[168:171], v[182:183], off
	v_or_b32_e32 v144, 48, v142
	v_ashrrev_i32_e32 v145, 31, v144
	v_lshlrev_b64 v[180:181], 12, v[144:145]
	v_lshlrev_b64 v[174:175], 11, v[142:143]
	v_lshlrev_b64 v[172:173], 11, v[172:173]
	v_lshl_add_u64 v[180:181], s[42:43], 0, v[180:181]
	v_lshl_add_u64 v[174:175], s[82:83], 0, v[174:175]
	v_lshl_add_u64 v[172:173], s[82:83], 0, v[172:173]
	v_lshl_add_u64 v[184:185], v[180:181], 0, v[140:141]
	v_lshl_add_u64 v[188:189], v[174:175], 0, v[140:141]
	v_lshl_add_u64 v[190:191], v[172:173], 0, v[140:141]
	global_load_dwordx4 v[172:175], v[182:183], off offset:256
	s_nop 0
	global_load_dwordx4 v[180:183], v[184:185], off
	s_nop 0
	global_load_dwordx4 v[184:187], v[184:185], off offset:256
	v_add_u32_e32 v234, 0x80, v142
	v_ashrrev_i32_e32 v235, 31, v234
	v_lshlrev_b64 v[236:237], 12, v[234:235]
	v_lshl_add_u64 v[236:237], s[42:43], 0, v[236:237]
	v_lshl_add_u64 v[236:237], v[236:237], 0, v[140:141]
	global_load_dwordx4 v[200:203], v[236:237], off
	global_load_dwordx4 v[204:207], v[236:237], off offset:256
	v_add_u32_e32 v234, 0x90, v142
	v_ashrrev_i32_e32 v235, 31, v234
	v_lshlrev_b64 v[236:237], 12, v[234:235]
	v_lshl_add_u64 v[236:237], s[42:43], 0, v[236:237]
	v_lshl_add_u64 v[236:237], v[236:237], 0, v[140:141]
	global_load_dwordx4 v[208:211], v[236:237], off
	global_load_dwordx4 v[212:215], v[236:237], off offset:256
	v_add_u32_e32 v234, 0xa0, v142
	v_ashrrev_i32_e32 v235, 31, v234
	v_lshlrev_b64 v[236:237], 12, v[234:235]
	v_lshl_add_u64 v[236:237], s[42:43], 0, v[236:237]
	v_lshl_add_u64 v[236:237], v[236:237], 0, v[140:141]
	global_load_dwordx4 v[216:219], v[236:237], off
	global_load_dwordx4 v[222:225], v[236:237], off offset:256
	v_add_u32_e32 v234, 0xb0, v142
	v_ashrrev_i32_e32 v235, 31, v234
	v_lshlrev_b64 v[236:237], 12, v[234:235]
	v_lshl_add_u64 v[236:237], s[42:43], 0, v[236:237]
	v_lshl_add_u64 v[236:237], v[236:237], 0, v[140:141]
	global_load_dwordx4 v[226:229], v[236:237], off
	global_load_dwordx4 v[230:233], v[236:237], off offset:256
	s_and_b64 vcc, exec, s[18:19]
	s_mov_b32 s38, s14
	s_mov_b32 s39, s12
	s_mov_b32 s15, s14
	s_mov_b32 s18, s12
	s_mov_b64 s[22:23], s[20:21]
	s_mov_b64 s[10:11], s[16:17]
	s_mov_b32 s13, s37
	s_nop 7
	s_nop 2
	s_waitcnt vmcnt(8)
	v_lshlrev_b32_e32 v194, 16, v154
	v_and_b32_e32 v195, 0xffff0000, v154
	v_lshlrev_b32_e32 v154, 16, v155
	v_and_b32_e32 v155, 0xffff0000, v155
	v_lshlrev_b32_e32 v196, 16, v156
	v_and_b32_e32 v197, 0xffff0000, v156
	v_lshlrev_b32_e32 v156, 16, v157
	v_and_b32_e32 v157, 0xffff0000, v157
	v_lshlrev_b32_e32 v198, 16, v158
	v_and_b32_e32 v199, 0xffff0000, v158
	v_lshlrev_b32_e32 v158, 16, v159
	v_and_b32_e32 v159, 0xffff0000, v159
	v_lshlrev_b32_e32 v192, 16, v152
	v_and_b32_e32 v193, 0xffff0000, v152
	v_lshlrev_b32_e32 v152, 16, v153
	v_and_b32_e32 v153, 0xffff0000, v153
	v_pk_mul_f32 v[120:121], v[120:121], v[194:195]
	v_pk_mul_f32 v[122:123], v[122:123], v[154:155]
	v_pk_mul_f32 v[118:119], v[118:119], v[156:157]
	v_pk_mul_f32 v[154:155], v[110:111], v[158:159]
	v_lshlrev_b32_e32 v156, 16, v160
	v_and_b32_e32 v157, 0xffff0000, v160
	v_lshlrev_b32_e32 v158, 16, v161
	v_and_b32_e32 v159, 0xffff0000, v161
	v_lshlrev_b32_e32 v160, 16, v162
	v_and_b32_e32 v161, 0xffff0000, v162
	v_lshlrev_b32_e32 v162, 16, v163
	v_and_b32_e32 v163, 0xffff0000, v163
	v_pk_mul_f32 v[124:125], v[124:125], v[192:193]
	v_pk_mul_f32 v[126:127], v[126:127], v[152:153]
	v_cvt_pk_bf16_f32 v110, v120, v121
	v_cvt_pk_bf16_f32 v111, v122, v123
	v_pk_mul_f32 v[112:113], v[112:113], v[156:157]
	v_pk_mul_f32 v[114:115], v[114:115], v[158:159]
	v_pk_mul_f32 v[120:121], v[104:105], v[160:161]
	v_pk_mul_f32 v[122:123], v[106:107], v[162:163]
	v_pk_mul_f32 v[116:117], v[116:117], v[196:197]
	v_pk_mul_f32 v[152:153], v[108:109], v[198:199]
	v_cvt_pk_bf16_f32 v108, v124, v125
	v_cvt_pk_bf16_f32 v109, v126, v127
	v_cvt_pk_bf16_f32 v104, v112, v113
	v_cvt_pk_bf16_f32 v105, v114, v115
	v_cvt_pk_bf16_f32 v106, v120, v121
	v_cvt_pk_bf16_f32 v107, v122, v123
	v_cvt_pk_bf16_f32 v116, v116, v117
	v_cvt_pk_bf16_f32 v117, v118, v119
	v_cvt_pk_bf16_f32 v118, v152, v153
	v_cvt_pk_bf16_f32 v119, v154, v155
	global_store_dwordx4 v[188:189], v[108:111], off
	global_store_dwordx4 v[188:189], v[116:119], off offset:256
	global_store_dwordx4 v[190:191], v[104:107], off
	v_lshlrev_b32_e32 v192, 16, v164
	v_and_b32_e32 v193, 0xffff0000, v164
	v_lshlrev_b32_e32 v104, 16, v165
	v_and_b32_e32 v105, 0xffff0000, v165
	v_pk_mul_f32 v[102:103], v[102:103], v[104:105]
	v_lshlrev_b32_e32 v104, 16, v166
	v_and_b32_e32 v105, 0xffff0000, v166
	v_pk_mul_f32 v[104:105], v[92:93], v[104:105]
	v_lshlrev_b32_e32 v92, 16, v167
	v_and_b32_e32 v93, 0xffff0000, v167
	v_pk_mul_f32 v[100:101], v[100:101], v[192:193]
	v_pk_mul_f32 v[106:107], v[94:95], v[92:93]
	v_cvt_pk_bf16_f32 v92, v100, v101
	v_cvt_pk_bf16_f32 v93, v102, v103
	v_cvt_pk_bf16_f32 v94, v104, v105
	v_cvt_pk_bf16_f32 v95, v106, v107
	global_store_dwordx4 v[190:191], v[92:95], off offset:256
	v_add_u32_e32 v102, 0xb0, v142
	v_ashrrev_i32_e32 v103, 31, v102
	v_lshlrev_b32_e32 v94, 16, v168
	v_and_b32_e32 v95, 0xffff0000, v168
	v_pk_mul_f32 v[94:95], v[96:97], v[94:95]
	v_lshlrev_b32_e32 v96, 16, v169
	v_and_b32_e32 v97, 0xffff0000, v169
	v_pk_mul_f32 v[96:97], v[98:99], v[96:97]
	v_lshlrev_b32_e32 v98, 16, v170
	v_and_b32_e32 v99, 0xffff0000, v170
	v_lshlrev_b64 v[92:93], 11, v[176:177]
	v_pk_mul_f32 v[98:99], v[88:89], v[98:99]
	v_lshlrev_b32_e32 v88, 16, v171
	v_and_b32_e32 v89, 0xffff0000, v171
	v_pk_mul_f32 v[100:101], v[90:91], v[88:89]
	v_lshl_add_u64 v[92:93], s[82:83], 0, v[92:93]
	v_cvt_pk_bf16_f32 v88, v94, v95
	v_cvt_pk_bf16_f32 v89, v96, v97
	v_cvt_pk_bf16_f32 v90, v98, v99
	v_cvt_pk_bf16_f32 v91, v100, v101
	v_lshl_add_u64 v[92:93], v[92:93], 0, v[140:141]
	global_store_dwordx4 v[92:93], v[88:91], off
	v_add_u32_e32 v96, 0x80, v142
	v_ashrrev_i32_e32 v97, 31, v96
	v_lshlrev_b32_e32 v88, 16, v172
	v_and_b32_e32 v89, 0xffff0000, v172
	v_pk_mul_f32 v[84:85], v[84:85], v[88:89]
	v_lshlrev_b32_e32 v88, 16, v173
	v_and_b32_e32 v89, 0xffff0000, v173
	v_pk_mul_f32 v[86:87], v[86:87], v[88:89]
	v_lshlrev_b32_e32 v88, 16, v174
	v_and_b32_e32 v89, 0xffff0000, v174
	v_pk_mul_f32 v[88:89], v[76:77], v[88:89]
	v_lshlrev_b32_e32 v76, 16, v175
	v_and_b32_e32 v77, 0xffff0000, v175
	v_pk_mul_f32 v[90:91], v[78:79], v[76:77]
	v_cvt_pk_bf16_f32 v76, v84, v85
	v_cvt_pk_bf16_f32 v77, v86, v87
	v_cvt_pk_bf16_f32 v78, v88, v89
	v_cvt_pk_bf16_f32 v79, v90, v91
	global_store_dwordx4 v[92:93], v[76:79], off offset:256
	v_add_u32_e32 v98, 0x90, v142
	v_ashrrev_i32_e32 v99, 31, v98
	v_lshlrev_b32_e32 v78, 16, v180
	v_and_b32_e32 v79, 0xffff0000, v180
	v_pk_mul_f32 v[78:79], v[80:81], v[78:79]
	v_lshlrev_b32_e32 v80, 16, v181
	v_and_b32_e32 v81, 0xffff0000, v181
	v_pk_mul_f32 v[80:81], v[82:83], v[80:81]
	v_lshlrev_b32_e32 v82, 16, v182
	v_and_b32_e32 v83, 0xffff0000, v182
	v_lshlrev_b64 v[76:77], 11, v[144:145]
	v_pk_mul_f32 v[82:83], v[72:73], v[82:83]
	v_lshlrev_b32_e32 v72, 16, v183
	v_and_b32_e32 v73, 0xffff0000, v183
	v_pk_mul_f32 v[84:85], v[74:75], v[72:73]
	v_lshl_add_u64 v[76:77], s[82:83], 0, v[76:77]
	v_cvt_pk_bf16_f32 v72, v78, v79
	v_cvt_pk_bf16_f32 v73, v80, v81
	v_cvt_pk_bf16_f32 v74, v82, v83
	v_cvt_pk_bf16_f32 v75, v84, v85
	v_lshl_add_u64 v[76:77], v[76:77], 0, v[140:141]
	global_store_dwordx4 v[76:77], v[72:75], off
	v_add_u32_e32 v100, 0xa0, v142
	v_ashrrev_i32_e32 v101, 31, v100
	v_lshlrev_b32_e32 v72, 16, v184
	v_and_b32_e32 v73, 0xffff0000, v184
	v_pk_mul_f32 v[68:69], v[68:69], v[72:73]
	v_lshlrev_b32_e32 v72, 16, v185
	v_and_b32_e32 v73, 0xffff0000, v185
	v_pk_mul_f32 v[70:71], v[70:71], v[72:73]
	v_lshlrev_b32_e32 v72, 16, v186
	v_and_b32_e32 v73, 0xffff0000, v186
	v_pk_mul_f32 v[72:73], v[64:65], v[72:73]
	v_lshlrev_b32_e32 v64, 16, v187
	v_and_b32_e32 v65, 0xffff0000, v187
	v_pk_mul_f32 v[74:75], v[66:67], v[64:65]
	v_cvt_pk_bf16_f32 v64, v68, v69
	v_cvt_pk_bf16_f32 v65, v70, v71
	v_cvt_pk_bf16_f32 v66, v72, v73
	v_cvt_pk_bf16_f32 v67, v74, v75
	global_store_dwordx4 v[76:77], v[64:67], off offset:256
	s_nop 1
	v_lshlrev_b64 v[64:65], 12, v[96:97]
	v_lshl_add_u64 v[64:65], s[42:43], 0, v[64:65]
	v_lshl_add_u64 v[64:65], v[64:65], 0, v[140:141]
	v_lshlrev_b64 v[64:65], 12, v[98:99]
	v_lshl_add_u64 v[64:65], s[42:43], 0, v[64:65]
	v_lshl_add_u64 v[64:65], v[64:65], 0, v[140:141]
	v_lshlrev_b64 v[64:65], 12, v[100:101]
	v_lshl_add_u64 v[64:65], s[42:43], 0, v[64:65]
	v_lshl_add_u64 v[64:65], v[64:65], 0, v[140:141]
	v_lshlrev_b64 v[64:65], 12, v[102:103]
	v_lshl_add_u64 v[64:65], s[42:43], 0, v[64:65]
	v_lshl_add_u64 v[64:65], v[64:65], 0, v[140:141]
	s_nop 0
	v_lshlrev_b64 v[96:97], 11, v[96:97]
	s_waitcnt vmcnt(8)
	v_lshlrev_b32_e32 v104, 16, v200
	v_and_b32_e32 v105, 0xffff0000, v200
	v_lshlrev_b32_e32 v68, 16, v201
	v_and_b32_e32 v69, 0xffff0000, v201
	v_pk_mul_f32 v[62:63], v[62:63], v[68:69]
	v_lshlrev_b32_e32 v68, 16, v202
	v_and_b32_e32 v69, 0xffff0000, v202
	v_pk_mul_f32 v[60:61], v[60:61], v[104:105]
	v_pk_mul_f32 v[68:69], v[56:57], v[68:69]
	v_lshlrev_b32_e32 v56, 16, v203
	v_and_b32_e32 v57, 0xffff0000, v203
	v_pk_mul_f32 v[70:71], v[58:59], v[56:57]
	v_cvt_pk_bf16_f32 v56, v60, v61
	v_lshl_add_u64 v[60:61], s[82:83], 0, v[96:97]
	v_cvt_pk_bf16_f32 v57, v62, v63
	v_cvt_pk_bf16_f32 v58, v68, v69
	v_cvt_pk_bf16_f32 v59, v70, v71
	v_lshl_add_u64 v[60:61], v[60:61], 0, v[140:141]
	global_store_dwordx4 v[60:61], v[56:59], off
	s_nop 1
	v_lshlrev_b32_e32 v56, 16, v204
	v_and_b32_e32 v57, 0xffff0000, v204
	v_pk_mul_f32 v[52:53], v[52:53], v[56:57]
	v_lshlrev_b32_e32 v56, 16, v205
	v_and_b32_e32 v57, 0xffff0000, v205
	v_pk_mul_f32 v[54:55], v[54:55], v[56:57]
	v_lshlrev_b32_e32 v56, 16, v206
	v_and_b32_e32 v57, 0xffff0000, v206
	v_pk_mul_f32 v[56:57], v[44:45], v[56:57]
	v_lshlrev_b32_e32 v44, 16, v207
	v_and_b32_e32 v45, 0xffff0000, v207
	v_pk_mul_f32 v[58:59], v[46:47], v[44:45]
	v_cvt_pk_bf16_f32 v44, v52, v53
	v_cvt_pk_bf16_f32 v45, v54, v55
	v_cvt_pk_bf16_f32 v46, v56, v57
	v_cvt_pk_bf16_f32 v47, v58, v59
	global_store_dwordx4 v[60:61], v[44:47], off offset:256
	s_nop 1
	v_lshlrev_b32_e32 v46, 16, v208
	v_and_b32_e32 v47, 0xffff0000, v208
	v_pk_mul_f32 v[46:47], v[48:49], v[46:47]
	v_lshlrev_b32_e32 v48, 16, v209
	v_and_b32_e32 v49, 0xffff0000, v209
	v_pk_mul_f32 v[48:49], v[50:51], v[48:49]
	v_lshlrev_b32_e32 v50, 16, v210
	v_and_b32_e32 v51, 0xffff0000, v210
	v_lshlrev_b64 v[44:45], 11, v[98:99]
	v_pk_mul_f32 v[50:51], v[40:41], v[50:51]
	v_lshlrev_b32_e32 v40, 16, v211
	v_and_b32_e32 v41, 0xffff0000, v211
	v_pk_mul_f32 v[52:53], v[42:43], v[40:41]
	v_lshl_add_u64 v[44:45], s[82:83], 0, v[44:45]
	v_cvt_pk_bf16_f32 v40, v46, v47
	v_cvt_pk_bf16_f32 v41, v48, v49
	v_cvt_pk_bf16_f32 v42, v50, v51
	v_cvt_pk_bf16_f32 v43, v52, v53
	v_lshl_add_u64 v[44:45], v[44:45], 0, v[140:141]
	global_store_dwordx4 v[44:45], v[40:43], off
	s_nop 1
	v_lshlrev_b32_e32 v40, 16, v212
	v_and_b32_e32 v41, 0xffff0000, v212
	v_pk_mul_f32 v[36:37], v[36:37], v[40:41]
	v_lshlrev_b32_e32 v40, 16, v213
	v_and_b32_e32 v41, 0xffff0000, v213
	v_pk_mul_f32 v[38:39], v[38:39], v[40:41]
	v_lshlrev_b32_e32 v40, 16, v214
	v_and_b32_e32 v41, 0xffff0000, v214
	v_pk_mul_f32 v[40:41], v[28:29], v[40:41]
	v_lshlrev_b32_e32 v28, 16, v215
	v_and_b32_e32 v29, 0xffff0000, v215
	v_pk_mul_f32 v[42:43], v[30:31], v[28:29]
	v_cvt_pk_bf16_f32 v28, v36, v37
	v_cvt_pk_bf16_f32 v29, v38, v39
	v_cvt_pk_bf16_f32 v30, v40, v41
	v_cvt_pk_bf16_f32 v31, v42, v43
	global_store_dwordx4 v[44:45], v[28:31], off offset:256
	s_nop 1
	v_lshlrev_b32_e32 v30, 16, v216
	v_and_b32_e32 v31, 0xffff0000, v216
	v_pk_mul_f32 v[30:31], v[32:33], v[30:31]
	v_lshlrev_b32_e32 v32, 16, v217
	v_and_b32_e32 v33, 0xffff0000, v217
	v_pk_mul_f32 v[32:33], v[34:35], v[32:33]
	v_lshlrev_b32_e32 v34, 16, v218
	v_and_b32_e32 v35, 0xffff0000, v218
	v_lshlrev_b64 v[28:29], 11, v[100:101]
	v_pk_mul_f32 v[34:35], v[24:25], v[34:35]
	v_lshlrev_b32_e32 v24, 16, v219
	v_and_b32_e32 v25, 0xffff0000, v219
	v_pk_mul_f32 v[36:37], v[26:27], v[24:25]
	v_lshl_add_u64 v[28:29], s[82:83], 0, v[28:29]
	v_cvt_pk_bf16_f32 v24, v30, v31
	v_cvt_pk_bf16_f32 v25, v32, v33
	v_cvt_pk_bf16_f32 v26, v34, v35
	v_cvt_pk_bf16_f32 v27, v36, v37
	v_lshl_add_u64 v[28:29], v[28:29], 0, v[140:141]
	global_store_dwordx4 v[28:29], v[24:27], off
	s_nop 1
	v_lshlrev_b32_e32 v24, 16, v222
	v_and_b32_e32 v25, 0xffff0000, v222
	v_pk_mul_f32 v[20:21], v[20:21], v[24:25]
	v_lshlrev_b32_e32 v24, 16, v223
	v_and_b32_e32 v25, 0xffff0000, v223
	v_pk_mul_f32 v[22:23], v[22:23], v[24:25]
	v_lshlrev_b32_e32 v24, 16, v224
	v_and_b32_e32 v25, 0xffff0000, v224
	v_pk_mul_f32 v[24:25], v[12:13], v[24:25]
	v_lshlrev_b32_e32 v12, 16, v225
	v_and_b32_e32 v13, 0xffff0000, v225
	v_pk_mul_f32 v[26:27], v[14:15], v[12:13]
	v_cvt_pk_bf16_f32 v12, v20, v21
	v_cvt_pk_bf16_f32 v13, v22, v23
	v_cvt_pk_bf16_f32 v14, v24, v25
	v_cvt_pk_bf16_f32 v15, v26, v27
	global_store_dwordx4 v[28:29], v[12:15], off offset:256
	s_nop 1
	v_lshlrev_b32_e32 v14, 16, v226
	v_and_b32_e32 v15, 0xffff0000, v226
	v_pk_mul_f32 v[14:15], v[16:17], v[14:15]
	v_lshlrev_b32_e32 v16, 16, v227
	v_and_b32_e32 v17, 0xffff0000, v227
	v_pk_mul_f32 v[16:17], v[18:19], v[16:17]
	v_lshlrev_b32_e32 v18, 16, v228
	v_and_b32_e32 v19, 0xffff0000, v228
	v_lshlrev_b64 v[12:13], 11, v[102:103]
	v_pk_mul_f32 v[18:19], v[8:9], v[18:19]
	v_lshlrev_b32_e32 v8, 16, v229
	v_and_b32_e32 v9, 0xffff0000, v229
	v_pk_mul_f32 v[20:21], v[10:11], v[8:9]
	v_lshl_add_u64 v[12:13], s[82:83], 0, v[12:13]
	v_cvt_pk_bf16_f32 v8, v14, v15
	v_cvt_pk_bf16_f32 v9, v16, v17
	v_cvt_pk_bf16_f32 v10, v18, v19
	v_cvt_pk_bf16_f32 v11, v20, v21
	v_lshl_add_u64 v[12:13], v[12:13], 0, v[140:141]
	global_store_dwordx4 v[12:13], v[8:11], off
	s_nop 1
	v_lshlrev_b32_e32 v8, 16, v230
	v_and_b32_e32 v9, 0xffff0000, v230
	v_pk_mul_f32 v[4:5], v[4:5], v[8:9]
	v_lshlrev_b32_e32 v8, 16, v231
	v_and_b32_e32 v9, 0xffff0000, v231
	v_pk_mul_f32 v[6:7], v[6:7], v[8:9]
	v_lshlrev_b32_e32 v8, 16, v232
	v_and_b32_e32 v9, 0xffff0000, v232
	v_pk_mul_f32 v[8:9], v[0:1], v[8:9]
	v_lshlrev_b32_e32 v0, 16, v233
	v_and_b32_e32 v1, 0xffff0000, v233
	v_pk_mul_f32 v[10:11], v[2:3], v[0:1]
	v_cvt_pk_bf16_f32 v0, v4, v5
	v_cvt_pk_bf16_f32 v1, v6, v7
	v_cvt_pk_bf16_f32 v2, v8, v9
	v_cvt_pk_bf16_f32 v3, v10, v11
	global_store_dwordx4 v[12:13], v[0:3], off offset:256
	s_cbranch_vccz .LBB0_1260
	s_waitcnt vmcnt(0)
	s_cmpk_gt_u32 s26, 0xff
	s_cbranch_scc1 .LBB0_1272
	s_barrier
